# static wave priority + GLA prep gate loop hand-scheduled (16 LDS reads issued together, 4 timestep chains interleaved, no s_nop padding; DUP x4: -9.7 us per pass) + thin GEMM early K loads
# speedup vs baseline: 1.0046x; 1.0014x over previous
; __device__ __forceinline__ float log_sigmoid_f(float z) { return fminf(z, 0.f) - __logf(1.0f + __expf(-fabsf(z))); }
; __device__ __forceinline__ void gla_prep_unit(const Params& P, LAS unsigned char* lds, int u) {
;     ...
;     float cum = 0.f;
; #pragma unroll 4
;     for (int tt = 0; tt < 32; ++tt) { const int t = 32 * th + tt; float z = bias;
; #pragma unroll
;         for (int j = 0; j < 16; ++j) z += GL[t * 16 + j] * w2[j];
;         cum += log_sigmoid_f(z) * (1.0f / 16.0f); Bs[t * 256 + c] = cum; }
.LBB0_360:
	v_add_u32_e32 v67, 0, v66
	s_add_i32 s7, s7, -4
	v_add_u32_e32 v66, 0x100, v66
	s_cmp_eq_u32 s7, 0
	v_add_u32_e32 v223, 0x20800, v67
	ds_read_b128 v[80:83], v223
	ds_read_b128 v[132:135], v223 offset:16
	ds_read_b128 v[136:139], v223 offset:32
	ds_read_b128 v[140:143], v223 offset:48
	ds_read_b128 v[144:147], v223 offset:64
	ds_read_b128 v[148:151], v223 offset:80
	ds_read_b128 v[152:155], v223 offset:96
	ds_read_b128 v[156:159], v223 offset:112
	ds_read_b128 v[160:163], v223 offset:128
	ds_read_b128 v[164:167], v223 offset:144
	ds_read_b128 v[168:171], v223 offset:160
	ds_read_b128 v[180:183], v223 offset:176
	ds_read_b128 v[184:187], v223 offset:192
	ds_read_b128 v[188:191], v223 offset:208
	ds_read_b128 v[192:195], v223 offset:224
	ds_read_b128 v[196:199], v223 offset:240
	v_add_u32_e32 v72, 0, v65
	v_add_u32_e32 v65, 0x1000, v65
	s_waitcnt vmcnt(0) lgkmcnt(0)
	v_fma_f32 v202, v57, v80, v63
	v_fma_f32 v206, v57, v144, v63
	v_fma_f32 v210, v57, v160, v63
	v_fma_f32 v214, v57, v184, v63
	v_fmac_f32_e32 v202, v58, v81
	v_fmac_f32_e32 v206, v58, v145
	v_fmac_f32_e32 v210, v58, v161
	v_fmac_f32_e32 v214, v58, v185
	v_fmac_f32_e32 v202, v59, v82
	v_fmac_f32_e32 v206, v59, v146
	v_fmac_f32_e32 v210, v59, v162
	v_fmac_f32_e32 v214, v59, v186
	v_fmac_f32_e32 v202, v60, v83
	v_fmac_f32_e32 v206, v60, v147
	v_fmac_f32_e32 v210, v60, v163
	v_fmac_f32_e32 v214, v60, v187
	v_fmac_f32_e32 v202, v61, v132
	v_fmac_f32_e32 v206, v61, v148
	v_fmac_f32_e32 v210, v61, v164
	v_fmac_f32_e32 v214, v61, v188
	v_fmac_f32_e32 v202, v62, v133
	v_fmac_f32_e32 v206, v62, v149
	v_fmac_f32_e32 v210, v62, v165
	v_fmac_f32_e32 v214, v62, v189
	v_pk_mul_f32 v[200:201], v[44:45], v[134:135]
	v_pk_mul_f32 v[204:205], v[44:45], v[150:151]
	v_pk_mul_f32 v[208:209], v[44:45], v[166:167]
	v_pk_mul_f32 v[212:213], v[44:45], v[190:191]
	v_add_f32_e32 v200, v202, v200
	v_add_f32_e32 v204, v206, v204
	v_add_f32_e32 v208, v210, v208
	v_add_f32_e32 v212, v214, v212
	v_add_f32_e32 v202, v200, v201
	v_add_f32_e32 v206, v204, v205
	v_add_f32_e32 v210, v208, v209
	v_add_f32_e32 v214, v212, v213
	v_pk_mul_f32 v[200:201], v[46:47], v[136:137]
	v_pk_mul_f32 v[204:205], v[46:47], v[152:153]
	v_pk_mul_f32 v[208:209], v[46:47], v[168:169]
	v_pk_mul_f32 v[212:213], v[46:47], v[192:193]
	v_add_f32_e32 v200, v202, v200
	v_add_f32_e32 v204, v206, v204
	v_add_f32_e32 v208, v210, v208
	v_add_f32_e32 v212, v214, v212
	v_add_f32_e32 v202, v200, v201
	v_add_f32_e32 v206, v204, v205
	v_add_f32_e32 v210, v208, v209
	v_add_f32_e32 v214, v212, v213
	v_pk_mul_f32 v[200:201], v[48:49], v[138:139]
	v_pk_mul_f32 v[204:205], v[48:49], v[154:155]
	v_pk_mul_f32 v[208:209], v[48:49], v[170:171]
	v_pk_mul_f32 v[212:213], v[48:49], v[194:195]
	v_add_f32_e32 v200, v202, v200
	v_add_f32_e32 v204, v206, v204
	v_add_f32_e32 v208, v210, v208
	v_add_f32_e32 v212, v214, v212
	v_add_f32_e32 v202, v200, v201
	v_add_f32_e32 v206, v204, v205
	v_add_f32_e32 v210, v208, v209
	v_add_f32_e32 v214, v212, v213
	v_pk_mul_f32 v[200:201], v[50:51], v[140:141]
	v_pk_mul_f32 v[204:205], v[50:51], v[156:157]
	v_pk_mul_f32 v[208:209], v[50:51], v[180:181]
	v_pk_mul_f32 v[212:213], v[50:51], v[196:197]
	v_add_f32_e32 v200, v202, v200
	v_add_f32_e32 v204, v206, v204
	v_add_f32_e32 v208, v210, v208
	v_add_f32_e32 v212, v214, v212
	v_add_f32_e32 v202, v200, v201
	v_add_f32_e32 v206, v204, v205
	v_add_f32_e32 v210, v208, v209
	v_add_f32_e32 v214, v212, v213
	v_pk_mul_f32 v[200:201], v[52:53], v[142:143]
	v_pk_mul_f32 v[204:205], v[52:53], v[158:159]
	v_pk_mul_f32 v[208:209], v[52:53], v[182:183]
	v_pk_mul_f32 v[212:213], v[52:53], v[198:199]
	v_add_f32_e32 v200, v202, v200
	v_add_f32_e32 v204, v206, v204
	v_add_f32_e32 v208, v210, v208
	v_add_f32_e32 v212, v214, v212
	v_add_f32_e32 v200, v200, v201
	v_add_f32_e32 v204, v204, v205
	v_add_f32_e32 v208, v208, v209
	v_add_f32_e32 v212, v212, v213
	v_min_f32_e32 v216, 0, v200
	v_min_f32_e32 v217, 0, v204
	v_min_f32_e32 v218, 0, v208
	v_min_f32_e32 v219, 0, v212
	v_mul_f32_e64 v200, |v200|, s19
	v_mul_f32_e64 v204, |v204|, s19
	v_mul_f32_e64 v208, |v208|, s19
	v_mul_f32_e64 v212, |v212|, s19
	v_exp_f32_e32 v200, v200
	v_exp_f32_e32 v204, v204
	v_exp_f32_e32 v208, v208
	v_exp_f32_e32 v212, v212
	v_add_f32_e32 v200, 1.0, v200
	v_add_f32_e32 v204, 1.0, v204
	v_add_f32_e32 v208, 1.0, v208
	v_add_f32_e32 v212, 1.0, v212
	v_cmp_gt_f32_e64 s[28:29], s20, v200
	v_cmp_gt_f32_e64 s[30:31], s20, v204
	v_cmp_gt_f32_e64 s[34:35], s20, v208
	v_cmp_gt_f32_e64 s[36:37], s20, v212
	v_cndmask_b32_e64 v203, 0, 32, s[28:29]
	v_cndmask_b32_e64 v207, 0, 32, s[30:31]
	v_cndmask_b32_e64 v211, 0, 32, s[34:35]
	v_cndmask_b32_e64 v215, 0, 32, s[36:37]
	v_ldexp_f32 v200, v200, v203
	v_ldexp_f32 v204, v204, v207
	v_ldexp_f32 v208, v208, v211
	v_ldexp_f32 v212, v212, v215
	v_log_f32_e32 v200, v200
	v_log_f32_e32 v204, v204
	v_log_f32_e32 v208, v208
	v_log_f32_e32 v212, v212
	v_mul_f32_e32 v203, 0x3f317217, v200
	v_mul_f32_e32 v207, 0x3f317217, v204
	v_mul_f32_e32 v211, 0x3f317217, v208
	v_mul_f32_e32 v215, 0x3f317217, v212
	v_fma_f32 v203, v200, s21, -v203
	v_fma_f32 v207, v204, s21, -v207
	v_fma_f32 v211, v208, s21, -v211
	v_fma_f32 v215, v212, s21, -v215
	v_fmac_f32_e32 v203, 0x3377d1cf, v200
	v_fmac_f32_e32 v207, 0x3377d1cf, v204
	v_fmac_f32_e32 v211, 0x3377d1cf, v208
	v_fmac_f32_e32 v215, 0x3377d1cf, v212
	v_fmac_f32_e32 v203, 0x3f317217, v200
	v_fmac_f32_e32 v207, 0x3f317217, v204
	v_fmac_f32_e32 v211, 0x3f317217, v208
	v_fmac_f32_e32 v215, 0x3f317217, v212
	v_cmp_lt_f32_e64 s[38:39], |v200|, s22
	v_cmp_lt_f32_e64 s[48:49], |v204|, s22
	v_cmp_lt_f32_e64 s[50:51], |v208|, s22
	v_cmp_lt_f32_e64 s[52:53], |v212|, s22
	v_cndmask_b32_e64 v200, v200, v203, s[38:39]
	v_cndmask_b32_e64 v204, v204, v207, s[48:49]
	v_cndmask_b32_e64 v208, v208, v211, s[50:51]
	v_cndmask_b32_e64 v212, v212, v215, s[52:53]
	v_cndmask_b32_e64 v203, 0, v54, s[28:29]
	v_cndmask_b32_e64 v207, 0, v54, s[30:31]
	v_cndmask_b32_e64 v211, 0, v54, s[34:35]
	v_cndmask_b32_e64 v215, 0, v54, s[36:37]
	v_sub_f32_e32 v200, v200, v203
	v_sub_f32_e32 v204, v204, v207
	v_sub_f32_e32 v208, v208, v211
	v_sub_f32_e32 v212, v212, v215
	v_sub_f32_e32 v200, v216, v200
	v_sub_f32_e32 v204, v217, v204
	v_sub_f32_e32 v208, v218, v208
	v_sub_f32_e32 v212, v219, v212
	v_fmac_f32_e32 v64, 0x3d800000, v200
	ds_write_b32 v72, v64
	v_fmac_f32_e32 v64, 0x3d800000, v204
	ds_write_b32 v72, v64 offset:1024
	v_fmac_f32_e32 v64, 0x3d800000, v208
	ds_write_b32 v72, v64 offset:2048
	v_fmac_f32_e32 v64, 0x3d800000, v212
	ds_write_b32 v72, v64 offset:3072
	s_cbranch_scc0 .LBB0_360
; #define LAS __attribute__((address_space(3)))
; __device__ __forceinline__ unsigned f2bf(float f) { return cvtpk(f, 0.f) & 0xffffu; }
; __device__ __forceinline__ void gla_prep_unit(const Params& P, LAS unsigned char* lds, int u) {
;     ...
;     TOT[th * 256 + c] = cum;
; #pragma unroll
;     for (int it = 0; it < 4; ++it) { const int idx = it * NTHREADS + tid, t = idx >> 5, cc = idx & 31; *(LAS v4u*)(QS + t * 264 + 8 * cc) = rq[it]; *(LAS v4u*)(KS + t * 264 + 8 * cc) = rk[it]; }
;     v4u rv[8];
; #pragma unroll
;     for (int it = 0; it < 8; ++it) { const int idx = it * NTHREADS + tid, t = idx >> 6, cc = idx & 63; rv[it] = __builtin_nontemporal_load((const v4u*)(PROJ + (size_t)(tok0 + t) * LD0 + 2048 + 512 * h + 8 * cc)); }
;     __syncthreads();
;     const float off = th ? TOT[c] : 0.f, blast = TOT[c] + TOT[256 + c], eblast = __expf(blast);
;     for (int g8 = 0; g8 < 4; ++g8) { unsigned kdp[8];
; #pragma unroll
;         for (int e = 0; e < 8; ++e) { const int t = 32 * th + g8 * 8 + e; const float bb = Bs[t * 256 + c] + off;
;             const float qv = bf2f(QS[t * 264 + c]), kv = bf2f(KS[t * 264 + c]);
;             const float eb = __expf(bb), qt = qv * 0.0625f * eb, kt = kv * __expf(-bb), kd = kt * eblast;
;             QS[t * 264 + c] = (bf16)f2bf(qt); KS[t * 264 + c] = (bf16)f2bf(kt); kdp[e] = f2bf(kd); }
;         v4u o; o.x = kdp[0] | (kdp[1] << 16); o.y = kdp[2] | (kdp[3] << 16); o.z = kdp[4] | (kdp[5] << 16); o.w = kdp[6] | (kdp[7] << 16);
;         *(v4u*)(KDT + ((size_t)u * 256 + c) * 64 + 32 * th + g8 * 8) = o; }
	v_lshl_add_u32 v44, v34, 2, s23
	ds_write_b32 v44, v64
	v_add_u32_e32 v44, s24, v32
	v_mul_lo_u32 v47, v42, s26
	v_add_u32_e32 v46, s25, v32
	v_add_u32_e32 v48, v44, v47
	ds_write_b128 v48, v[4:7]
	v_add_u32_e32 v4, v46, v47
	ds_write_b128 v4, v[0:3]
	v_mul_lo_u32 v0, v40, s26
	v_add_u32_e32 v1, v44, v0
	v_add_u32_e32 v0, v46, v0
	ds_write_b128 v0, v[8:11]
	v_mul_lo_u32 v0, v38, s26
	ds_write_b128 v1, v[12:15]
	v_add_u32_e32 v1, v44, v0
	v_add_u32_e32 v0, v46, v0
	ds_write_b128 v0, v[16:19]
	v_mul_lo_u32 v0, v36, s26
	v_readlane_b32 s0, v237, 52
	v_ashrrev_i32_e32 v45, 6, v34
	ds_write_b128 v1, v[20:23]
	v_add_u32_e32 v1, v44, v0
	v_add_u32_e32 v0, v46, v0
	v_readlane_b32 s1, v237, 53
	ds_write_b128 v1, v[28:31]
	ds_write_b128 v0, v[24:27]
	v_add_u32_e32 v0, s12, v45
	v_mov_b64_e32 v[28:29], s[0:1]
	v_and_b32_e32 v2, 0x1f8, v56
	v_mad_i64_i32 v[0:1], s[0:1], v0, s16, v[28:29]
	s_lshl_b32 s2, s2, 10
	v_ashrrev_i32_e32 v4, 6, v41
	v_lshl_add_u64 v[0:1], v[0:1], 0, s[2:3]
	v_lshlrev_b32_e32 v30, 1, v2
	v_mov_b32_e32 v31, v33
	v_add_u32_e32 v4, s12, v4
	v_lshl_add_u64 v[0:1], v[0:1], 0, v[30:31]
	v_mad_i64_i32 v[4:5], s[0:1], v4, s16, v[28:29]
	v_ashrrev_i32_e32 v8, 6, v39
	v_add_co_u32_e32 v0, vcc, s18, v0
	v_lshl_add_u64 v[4:5], v[4:5], 0, s[2:3]
	v_add_u32_e32 v8, s12, v8
	v_addc_co_u32_e32 v1, vcc, 0, v1, vcc
	v_lshl_add_u64 v[4:5], v[4:5], 0, v[30:31]
	v_mad_i64_i32 v[8:9], s[0:1], v8, s16, v[28:29]
	v_ashrrev_i32_e32 v12, 6, v37
	v_add_co_u32_e32 v4, vcc, s18, v4
	v_lshl_add_u64 v[8:9], v[8:9], 0, s[2:3]
	v_add_u32_e32 v12, s12, v12
	v_add_u32_e32 v48, 0x800, v34
	v_addc_co_u32_e32 v5, vcc, 0, v5, vcc
	v_lshl_add_u64 v[8:9], v[8:9], 0, v[30:31]
	v_mad_i64_i32 v[12:13], s[0:1], v12, s16, v[28:29]
	v_ashrrev_i32_e32 v16, 6, v48
	v_add_co_u32_e32 v8, vcc, s18, v8
	v_lshl_add_u64 v[12:13], v[12:13], 0, s[2:3]
	v_add_u32_e32 v16, s12, v16
	v_add_u32_e32 v49, 0xa00, v34
	v_addc_co_u32_e32 v9, vcc, 0, v9, vcc
	v_lshl_add_u64 v[12:13], v[12:13], 0, v[30:31]
	v_mad_i64_i32 v[16:17], s[0:1], v16, s16, v[28:29]
	v_ashrrev_i32_e32 v20, 6, v49
	v_add_co_u32_e32 v12, vcc, s18, v12
	v_lshl_add_u64 v[16:17], v[16:17], 0, s[2:3]
	v_add_u32_e32 v20, s12, v20
	v_add_u32_e32 v50, 0xc00, v34
	v_addc_co_u32_e32 v13, vcc, 0, v13, vcc
	v_lshl_add_u64 v[16:17], v[16:17], 0, v[30:31]
	v_mad_i64_i32 v[20:21], s[0:1], v20, s16, v[28:29]
	v_ashrrev_i32_e32 v24, 6, v50
	v_add_co_u32_e32 v16, vcc, s18, v16
	v_lshl_add_u64 v[20:21], v[20:21], 0, s[2:3]
	v_add_u32_e32 v24, s12, v24
	v_add_u32_e32 v51, 0xe00, v34
	v_addc_co_u32_e32 v17, vcc, 0, v17, vcc
	v_lshl_add_u64 v[20:21], v[20:21], 0, v[30:31]
	v_mad_i64_i32 v[24:25], s[0:1], v24, s16, v[28:29]
	v_ashrrev_i32_e32 v46, 6, v51
	v_add_co_u32_e32 v20, vcc, s18, v20
	v_lshl_add_u64 v[24:25], v[24:25], 0, s[2:3]
	v_add_u32_e32 v46, s12, v46
	v_addc_co_u32_e32 v21, vcc, 0, v21, vcc
	v_lshl_add_u64 v[24:25], v[24:25], 0, v[30:31]
	v_mad_i64_i32 v[28:29], s[0:1], v46, s16, v[28:29]
	v_add_co_u32_e32 v24, vcc, s18, v24
	v_lshl_add_u64 v[28:29], v[28:29], 0, s[2:3]
	s_nop 0
	v_addc_co_u32_e32 v25, vcc, 0, v25, vcc
	v_lshl_add_u64 v[28:29], v[28:29], 0, v[30:31]
	v_add_co_u32_e32 v28, vcc, s18, v28
	v_and_b32_e32 v58, 0xffffffe0, v55
	v_add_u32_e32 v62, 0, v43
	v_addc_co_u32_e32 v29, vcc, 0, v29, vcc
	v_add_u32_e32 v46, s23, v43
	global_load_dwordx4 v[0:3], v[0:1], off nt
	v_lshl_add_u32 v61, v58, 10, v62
	global_load_dwordx4 v[4:7], v[4:5], off nt
	v_cmp_gt_u32_e32 vcc, s17, v34
	global_load_dwordx4 v[8:11], v[8:9], off nt
	s_ashr_i32 s7, s6, 31
	global_load_dwordx4 v[12:15], v[12:13], off nt
	s_lshl_b64 s[0:1], s[6:7], 15
	global_load_dwordx4 v[16:19], v[16:17], off nt
	s_add_u32 s12, s33, s0
	global_load_dwordx4 v[20:23], v[20:21], off nt
	s_addc_u32 s13, s56, s1
	global_load_dwordx4 v[24:27], v[24:25], off nt
	v_ashrrev_i32_e32 v59, 31, v58
	global_load_dwordx4 v[28:31], v[28:29], off nt
	s_waitcnt lgkmcnt(0)
	s_barrier
	ds_read2st64_b32 v[46:47], v46 offset1:4
	ds_read2st64_b32 v[56:57], v61 offset1:4
	s_waitcnt lgkmcnt(1)
	v_cndmask_b32_e64 v63, v46, 0, vcc
	v_add_f32_e32 v46, v46, v47
	v_mul_f32_e32 v46, 0x3fb8aa3b, v46
	s_waitcnt lgkmcnt(0)
	v_add_f32_e32 v53, v63, v56
	v_mul_lo_u32 v56, v58, s27
	v_exp_f32_e32 v52, v46
	v_lshlrev_b32_e32 v46, 7, v35
	v_mov_b32_e32 v47, v33
	v_or_b32_e32 v56, v56, v35
	v_lshl_add_u64 v[46:47], s[12:13], 0, v[46:47]
	v_lshlrev_b32_e32 v56, 1, v56
	v_lshl_add_u64 v[46:47], v[58:59], 1, v[46:47]
	v_add_u32_e32 v58, s24, v56
	ds_read_u16 v59, v58
	v_add_u32_e32 v60, s25, v56
	ds_read_u16 v64, v60
	v_mul_f32_e32 v65, 0x3fb8aa3b, v53
	v_mul_f32_e32 v53, 0xbfb8aa3b, v53
	v_exp_f32_e32 v65, v65
	v_exp_f32_e32 v53, v53
	s_waitcnt lgkmcnt(1)
	v_lshlrev_b32_e32 v59, 16, v59
	s_waitcnt lgkmcnt(0)
	v_lshlrev_b32_e32 v64, 16, v64
	v_mul_f32_e32 v59, 0x3d800000, v59
	v_mul_f32_e32 v59, v65, v59
	v_mul_f32_e32 v53, v53, v64
	v_mul_f32_e32 v64, v52, v53
	v_cvt_pk_bf16_f32 v59, v59, s0
	v_cvt_pk_bf16_f32 v53, v53, s0
	v_add_u32_e32 v56, 0x210, v56
	ds_write_b16 v58, v59
	ds_write_b16 v60, v53
	v_cvt_pk_bf16_f32 v53, v64, 0
	v_add_u32_e32 v64, s24, v56
	ds_read_u16 v58, v64
	v_add_u32_e32 v65, s25, v56
	v_add_f32_e32 v57, v63, v57
	ds_read_u16 v56, v65
	v_mul_f32_e32 v59, 0x3fb8aa3b, v57
	v_mul_f32_e32 v57, 0xbfb8aa3b, v57
	v_exp_f32_e32 v59, v59
	v_exp_f32_e32 v57, v57
	s_waitcnt lgkmcnt(1)
	v_lshlrev_b32_e32 v58, 16, v58
	s_waitcnt lgkmcnt(0)
	v_lshlrev_b32_e32 v56, 16, v56
	v_mul_f32_e32 v58, 0x3d800000, v58
	v_mul_f32_e32 v58, v59, v58
	v_mul_f32_e32 v56, v57, v56
	v_mul_f32_e32 v57, v52, v56
	v_cvt_pk_bf16_f32 v58, v58, s0
	v_cvt_pk_bf16_f32 v56, v56, s0
	ds_write_b16 v64, v58
	ds_write_b16 v65, v56
	v_cvt_pk_bf16_f32 v58, v57, 0
	ds_read2st64_b32 v[56:57], v61 offset0:8 offset1:12
	ds_read_u16 v59, v64 offset:528
	ds_read_u16 v60, v65 offset:528
	ds_read_u16 v67, v65 offset:1584
	ds_read_u16 v69, v65 offset:2640
	s_waitcnt lgkmcnt(4)
; __device__ __forceinline__ unsigned f2bf(float f) { return cvtpk(f, 0.f) & 0xffffu; }
; __device__ __forceinline__ void gla_prep_unit(const Params& P, LAS unsigned char* lds, int u) {
;     ...
;     for (int g8 = 0; g8 < 4; ++g8) { unsigned kdp[8];
; #pragma unroll
;         for (int e = 0; e < 8; ++e) { const int t = 32 * th + g8 * 8 + e; const float bb = Bs[t * 256 + c] + off;
;             const float qv = bf2f(QS[t * 264 + c]), kv = bf2f(KS[t * 264 + c]);
;             const float eb = __expf(bb), qt = qv * 0.0625f * eb, kt = kv * __expf(-bb), kd = kt * eblast;
;             QS[t * 264 + c] = (bf16)f2bf(qt); KS[t * 264 + c] = (bf16)f2bf(kt); kdp[e] = f2bf(kd); }
;         v4u o; o.x = kdp[0] | (kdp[1] << 16); o.y = kdp[2] | (kdp[3] << 16); o.z = kdp[4] | (kdp[5] << 16); o.w = kdp[6] | (kdp[7] << 16);
;         *(v4u*)(KDT + ((size_t)u * 256 + c) * 64 + 32 * th + g8 * 8) = o; }
	v_add_f32_e32 v56, v63, v56
	v_mul_f32_e32 v66, 0x3fb8aa3b, v56
	v_mul_f32_e32 v56, 0xbfb8aa3b, v56
	v_exp_f32_e32 v56, v56
	v_exp_f32_e32 v66, v66
	s_waitcnt lgkmcnt(3)
	v_lshlrev_b32_e32 v59, 16, v59
	s_waitcnt lgkmcnt(2)
	v_lshlrev_b32_e32 v60, 16, v60
	v_mul_f32_e32 v59, 0x3d800000, v59
	v_mul_f32_e32 v56, v56, v60
	v_mul_f32_e32 v59, v66, v59
	v_mul_f32_e32 v60, v52, v56
	v_cvt_pk_bf16_f32 v56, v56, s0
	v_cvt_pk_bf16_f32 v59, v59, s0
	ds_write_b16 v65, v56 offset:528
	v_cvt_pk_bf16_f32 v56, v60, 0
	ds_write_b16 v64, v59 offset:528
	v_and_b32_e32 v59, 0xffff, v56
	v_add_f32_e32 v56, v63, v57
	ds_read_u16 v57, v64 offset:1056
	ds_read_u16 v60, v65 offset:1056
	v_mul_f32_e32 v66, 0x3fb8aa3b, v56
	v_mul_f32_e32 v56, 0xbfb8aa3b, v56
	v_exp_f32_e32 v66, v66
	v_exp_f32_e32 v56, v56
	s_waitcnt lgkmcnt(1)
	v_lshlrev_b32_e32 v57, 16, v57
	s_waitcnt lgkmcnt(0)
	v_lshlrev_b32_e32 v60, 16, v60
	v_mul_f32_e32 v57, 0x3d800000, v57
	v_mul_f32_e32 v57, v66, v57
	v_mul_f32_e32 v56, v56, v60
	v_mul_f32_e32 v60, v52, v56
	v_cvt_pk_bf16_f32 v57, v57, s0
	v_cvt_pk_bf16_f32 v56, v56, s0
	ds_write_b16 v64, v57 offset:1056
	ds_write_b16 v65, v56 offset:1056
	ds_read2st64_b32 v[56:57], v61 offset0:16 offset1:20
	ds_read_u16 v66, v64 offset:1584
	v_lshlrev_b32_e32 v67, 16, v67
	v_lshlrev_b32_e32 v69, 16, v69
	v_and_b32_e32 v53, 0xffff, v53
	s_waitcnt lgkmcnt(1)
	v_add_f32_e32 v56, v63, v56
	v_mul_f32_e32 v68, 0x3fb8aa3b, v56
	v_mul_f32_e32 v56, 0xbfb8aa3b, v56
	v_exp_f32_e32 v56, v56
	v_exp_f32_e32 v68, v68
	s_waitcnt lgkmcnt(0)
	v_lshlrev_b32_e32 v66, 16, v66
	v_mul_f32_e32 v66, 0x3d800000, v66
	v_mul_f32_e32 v56, v56, v67
	v_mul_f32_e32 v66, v68, v66
	v_mul_f32_e32 v67, v52, v56
	v_cvt_pk_bf16_f32 v56, v56, s0
	v_cvt_pk_bf16_f32 v66, v66, s0
	ds_write_b16 v65, v56 offset:1584
	v_cvt_pk_bf16_f32 v56, v67, 0
	ds_write_b16 v64, v66 offset:1584
	v_and_b32_e32 v66, 0xffff, v56
	v_add_f32_e32 v56, v63, v57
	ds_read_u16 v57, v64 offset:2112
	ds_read_u16 v67, v65 offset:2112
	v_mul_f32_e32 v68, 0x3fb8aa3b, v56
	v_mul_f32_e32 v56, 0xbfb8aa3b, v56
	v_exp_f32_e32 v68, v68
	v_exp_f32_e32 v56, v56
	s_waitcnt lgkmcnt(1)
	v_lshlrev_b32_e32 v57, 16, v57
	s_waitcnt lgkmcnt(0)
	v_lshlrev_b32_e32 v67, 16, v67
	v_mul_f32_e32 v57, 0x3d800000, v57
	v_mul_f32_e32 v57, v68, v57
	v_mul_f32_e32 v56, v56, v67
	v_mul_f32_e32 v67, v52, v56
	v_cvt_pk_bf16_f32 v57, v57, s0
	v_cvt_pk_bf16_f32 v56, v56, s0
	ds_write_b16 v64, v57 offset:2112
	ds_write_b16 v65, v56 offset:2112
	ds_read2st64_b32 v[56:57], v61 offset0:24 offset1:28
	ds_read_u16 v68, v64 offset:2640
	v_cvt_pk_bf16_f32 v60, v60, 0
	v_cvt_pk_bf16_f32 v67, v67, 0
	s_waitcnt lgkmcnt(1)
	v_add_f32_e32 v56, v63, v56
	v_mul_f32_e32 v70, 0x3fb8aa3b, v56
	v_mul_f32_e32 v56, 0xbfb8aa3b, v56
	v_exp_f32_e32 v56, v56
	v_exp_f32_e32 v70, v70
	s_waitcnt lgkmcnt(0)
	v_lshlrev_b32_e32 v68, 16, v68
	v_mul_f32_e32 v68, 0x3d800000, v68
	v_mul_f32_e32 v56, v56, v69
	v_mul_f32_e32 v68, v70, v68
	v_mul_f32_e32 v69, v52, v56
	v_cvt_pk_bf16_f32 v56, v56, s0
	v_cvt_pk_bf16_f32 v68, v68, s0
	ds_write_b16 v65, v56 offset:2640
	v_cvt_pk_bf16_f32 v56, v69, 0
	ds_write_b16 v64, v68 offset:2640
	v_and_b32_e32 v68, 0xffff, v56
	v_add_f32_e32 v56, v63, v57
	ds_read_u16 v57, v64 offset:3168
	ds_read_u16 v69, v65 offset:3168
	v_mul_f32_e32 v70, 0x3fb8aa3b, v56
	v_mul_f32_e32 v56, 0xbfb8aa3b, v56
	v_exp_f32_e32 v56, v56
	v_exp_f32_e32 v70, v70
	s_waitcnt lgkmcnt(1)
	v_lshlrev_b32_e32 v57, 16, v57
	s_waitcnt lgkmcnt(0)
	v_lshlrev_b32_e32 v69, 16, v69
	v_mul_f32_e32 v57, 0x3d800000, v57
	v_mul_f32_e32 v56, v56, v69
	v_mul_f32_e32 v57, v70, v57
	v_mul_f32_e32 v69, v52, v56
	v_cvt_pk_bf16_f32 v57, v57, s0
	v_cvt_pk_bf16_f32 v56, v56, s0
	v_cvt_pk_bf16_f32 v69, v69, 0
	ds_write_b16 v64, v57 offset:3168
	ds_write_b16 v65, v56 offset:3168
	v_lshl_or_b32 v56, v58, 16, v53
	v_lshl_or_b32 v57, v60, 16, v59
	v_lshl_or_b32 v58, v67, 16, v66
	v_lshl_or_b32 v59, v69, 16, v68
	global_store_dwordx4 v[46:47], v[56:59], off
	ds_read2st64_b32 v[56:57], v61 offset0:32 offset1:36
	ds_read_u16 v58, v65 offset:3696
	s_waitcnt lgkmcnt(1)
	v_add_f32_e32 v53, v63, v56
	ds_read_u16 v56, v64 offset:3696
	v_mul_f32_e32 v59, 0x3fb8aa3b, v53
	v_exp_f32_e32 v59, v59
	v_mul_f32_e32 v53, 0xbfb8aa3b, v53
	v_exp_f32_e32 v53, v53
	s_waitcnt lgkmcnt(0)
	v_lshlrev_b32_e32 v56, 16, v56
	v_mul_f32_e32 v56, 0x3d800000, v56
	v_lshlrev_b32_e32 v58, 16, v58
	v_mul_f32_e32 v56, v59, v56
	v_mul_f32_e32 v53, v53, v58
	v_cvt_pk_bf16_f32 v56, v56, s0
	v_mul_f32_e32 v58, v52, v53
	ds_write_b16 v64, v56 offset:3696
	v_cvt_pk_bf16_f32 v53, v53, s0
	v_add_f32_e32 v56, v63, v57
	ds_read_u16 v57, v64 offset:4224
	ds_write_b16 v65, v53 offset:3696
	v_cvt_pk_bf16_f32 v53, v58, 0
	ds_read_u16 v58, v65 offset:4224
	v_mul_f32_e32 v59, 0x3fb8aa3b, v56
	v_mul_f32_e32 v56, 0xbfb8aa3b, v56
	v_exp_f32_e32 v59, v59
	v_exp_f32_e32 v56, v56
	s_waitcnt lgkmcnt(2)
	v_lshlrev_b32_e32 v57, 16, v57
	s_waitcnt lgkmcnt(0)
	v_lshlrev_b32_e32 v58, 16, v58
	v_mul_f32_e32 v57, 0x3d800000, v57
	v_mul_f32_e32 v57, v59, v57
	v_mul_f32_e32 v56, v56, v58
	v_mul_f32_e32 v58, v52, v56
	v_cvt_pk_bf16_f32 v57, v57, s0
	v_cvt_pk_bf16_f32 v56, v56, s0
	ds_write_b16 v64, v57 offset:4224
	ds_write_b16 v65, v56 offset:4224
	ds_read2st64_b32 v[56:57], v61 offset0:40 offset1:44
	ds_read_u16 v59, v64 offset:4752
	ds_read_u16 v60, v65 offset:4752
	v_and_b32_e32 v53, 0xffff, v53
	v_cvt_pk_bf16_f32 v58, v58, 0
	s_waitcnt lgkmcnt(2)
	v_add_f32_e32 v56, v63, v56
	v_mul_f32_e32 v66, 0x3fb8aa3b, v56
	v_exp_f32_e32 v66, v66
	s_waitcnt lgkmcnt(1)
; __device__ __forceinline__ unsigned f2bf(float f) { return cvtpk(f, 0.f) & 0xffffu; }
; __device__ __forceinline__ void gla_prep_unit(const Params& P, LAS unsigned char* lds, int u) {
;     ...
;     for (int g8 = 0; g8 < 4; ++g8) { unsigned kdp[8];
; #pragma unroll
;         for (int e = 0; e < 8; ++e) { const int t = 32 * th + g8 * 8 + e; const float bb = Bs[t * 256 + c] + off;
;             const float qv = bf2f(QS[t * 264 + c]), kv = bf2f(KS[t * 264 + c]);
;             const float eb = __expf(bb), qt = qv * 0.0625f * eb, kt = kv * __expf(-bb), kd = kt * eblast;
;             QS[t * 264 + c] = (bf16)f2bf(qt); KS[t * 264 + c] = (bf16)f2bf(kt); kdp[e] = f2bf(kd); }
;         v4u o; o.x = kdp[0] | (kdp[1] << 16); o.y = kdp[2] | (kdp[3] << 16); o.z = kdp[4] | (kdp[5] << 16); o.w = kdp[6] | (kdp[7] << 16);
;         *(v4u*)(KDT + ((size_t)u * 256 + c) * 64 + 32 * th + g8 * 8) = o; }
	v_lshlrev_b32_e32 v59, 16, v59
	v_mul_f32_e32 v59, 0x3d800000, v59
	v_mul_f32_e32 v56, 0xbfb8aa3b, v56
	v_mul_f32_e32 v59, v66, v59
	v_exp_f32_e32 v56, v56
	v_cvt_pk_bf16_f32 v59, v59, s0
	ds_write_b16 v64, v59 offset:4752
	ds_read_u16 v67, v65 offset:5808
	s_waitcnt lgkmcnt(2)
	v_lshlrev_b32_e32 v60, 16, v60
	v_mul_f32_e32 v56, v56, v60
	v_mul_f32_e32 v60, v52, v56
	v_cvt_pk_bf16_f32 v56, v56, s0
	ds_write_b16 v65, v56 offset:4752
	v_cvt_pk_bf16_f32 v56, v60, 0
	v_and_b32_e32 v59, 0xffff, v56
	v_add_f32_e32 v56, v63, v57
	ds_read_u16 v57, v64 offset:5280
	ds_read_u16 v60, v65 offset:5280
	ds_read_u16 v69, v65 offset:6864
	v_mul_f32_e32 v66, 0x3fb8aa3b, v56
	v_mul_f32_e32 v56, 0xbfb8aa3b, v56
	v_exp_f32_e32 v66, v66
	v_exp_f32_e32 v56, v56
	s_waitcnt lgkmcnt(2)
	v_lshlrev_b32_e32 v57, 16, v57
	s_waitcnt lgkmcnt(1)
	v_lshlrev_b32_e32 v60, 16, v60
	v_mul_f32_e32 v57, 0x3d800000, v57
	v_mul_f32_e32 v57, v66, v57
	v_mul_f32_e32 v56, v56, v60
	v_mul_f32_e32 v60, v52, v56
	v_cvt_pk_bf16_f32 v57, v57, s0
	v_cvt_pk_bf16_f32 v56, v56, s0
	ds_write_b16 v64, v57 offset:5280
	ds_write_b16 v65, v56 offset:5280
	ds_read2st64_b32 v[56:57], v61 offset0:48 offset1:52
	ds_read_u16 v66, v64 offset:5808
	v_lshlrev_b32_e32 v67, 16, v67
	s_waitcnt lgkmcnt(4)
	v_lshlrev_b32_e32 v69, 16, v69
	v_cvt_pk_bf16_f32 v60, v60, 0
	s_waitcnt lgkmcnt(1)
	v_add_f32_e32 v56, v63, v56
	v_mul_f32_e32 v68, 0x3fb8aa3b, v56
	v_mul_f32_e32 v56, 0xbfb8aa3b, v56
	v_exp_f32_e32 v56, v56
	v_exp_f32_e32 v68, v68
	s_waitcnt lgkmcnt(0)
	v_lshlrev_b32_e32 v66, 16, v66
	v_mul_f32_e32 v66, 0x3d800000, v66
	v_mul_f32_e32 v56, v56, v67
	v_mul_f32_e32 v66, v68, v66
	v_mul_f32_e32 v67, v52, v56
	v_cvt_pk_bf16_f32 v56, v56, s0
	v_cvt_pk_bf16_f32 v66, v66, s0
	ds_write_b16 v65, v56 offset:5808
	v_cvt_pk_bf16_f32 v56, v67, 0
	ds_write_b16 v64, v66 offset:5808
	v_and_b32_e32 v66, 0xffff, v56
	v_add_f32_e32 v56, v63, v57
	ds_read_u16 v57, v64 offset:6336
	ds_read_u16 v67, v65 offset:6336
	v_mul_f32_e32 v68, 0x3fb8aa3b, v56
	v_mul_f32_e32 v56, 0xbfb8aa3b, v56
	v_exp_f32_e32 v68, v68
	v_exp_f32_e32 v56, v56
	s_waitcnt lgkmcnt(1)
	v_lshlrev_b32_e32 v57, 16, v57
	s_waitcnt lgkmcnt(0)
	v_lshlrev_b32_e32 v67, 16, v67
	v_mul_f32_e32 v57, 0x3d800000, v57
	v_mul_f32_e32 v57, v68, v57
	v_mul_f32_e32 v56, v56, v67
	v_mul_f32_e32 v67, v52, v56
	v_cvt_pk_bf16_f32 v57, v57, s0
	v_cvt_pk_bf16_f32 v56, v56, s0
	ds_write_b16 v64, v57 offset:6336
	ds_write_b16 v65, v56 offset:6336
	ds_read2st64_b32 v[56:57], v61 offset0:56 offset1:60
	ds_read_u16 v68, v64 offset:6864
	v_cvt_pk_bf16_f32 v67, v67, 0
	s_waitcnt lgkmcnt(1)
	v_add_f32_e32 v56, v63, v56
	v_mul_f32_e32 v70, 0x3fb8aa3b, v56
	v_mul_f32_e32 v56, 0xbfb8aa3b, v56
	v_exp_f32_e32 v56, v56
	v_exp_f32_e32 v70, v70
	s_waitcnt lgkmcnt(0)
	v_lshlrev_b32_e32 v68, 16, v68
	v_mul_f32_e32 v68, 0x3d800000, v68
	v_mul_f32_e32 v56, v56, v69
	v_mul_f32_e32 v68, v70, v68
	v_mul_f32_e32 v69, v52, v56
	v_cvt_pk_bf16_f32 v56, v56, s0
	v_cvt_pk_bf16_f32 v68, v68, s0
	ds_write_b16 v65, v56 offset:6864
	v_cvt_pk_bf16_f32 v56, v69, 0
	ds_write_b16 v64, v68 offset:6864
	v_and_b32_e32 v68, 0xffff, v56
	v_add_f32_e32 v56, v63, v57
	ds_read_u16 v57, v64 offset:7392
	v_mul_f32_e32 v70, 0x3fb8aa3b, v56
	v_exp_f32_e32 v70, v70
	ds_read_u16 v69, v65 offset:7392
	v_mul_f32_e32 v56, 0xbfb8aa3b, v56
	s_waitcnt lgkmcnt(1)
	v_lshlrev_b32_e32 v57, 16, v57
	v_mul_f32_e32 v57, 0x3d800000, v57
	v_exp_f32_e32 v56, v56
	v_mul_f32_e32 v57, v70, v57
	v_cvt_pk_bf16_f32 v57, v57, s0
	ds_write_b16 v64, v57 offset:7392
	v_lshl_or_b32 v57, v60, 16, v59
	ds_read_u16 v60, v65 offset:8976
	s_waitcnt lgkmcnt(2)
	v_lshlrev_b32_e32 v69, 16, v69
	v_mul_f32_e32 v56, v56, v69
	v_mul_f32_e32 v69, v52, v56
	v_cvt_pk_bf16_f32 v56, v56, s0
	v_cvt_pk_bf16_f32 v69, v69, 0
	ds_write_b16 v65, v56 offset:7392
	v_lshl_or_b32 v56, v58, 16, v53
	v_lshl_or_b32 v58, v67, 16, v66
	v_lshl_or_b32 v59, v69, 16, v68
	global_store_dwordx4 v[46:47], v[56:59], off offset:16
	ds_read2st64_b32 v[56:57], v61 offset0:64 offset1:68
	ds_read_u16 v58, v65 offset:7920
	s_waitcnt lgkmcnt(3)
	v_lshlrev_b32_e32 v60, 16, v60
	s_waitcnt lgkmcnt(1)
	v_add_f32_e32 v53, v63, v56
	ds_read_u16 v56, v64 offset:7920
	v_mul_f32_e32 v59, 0x3fb8aa3b, v53
	v_exp_f32_e32 v59, v59
	v_mul_f32_e32 v53, 0xbfb8aa3b, v53
	v_exp_f32_e32 v53, v53
	s_waitcnt lgkmcnt(0)
	v_lshlrev_b32_e32 v56, 16, v56
	v_mul_f32_e32 v56, 0x3d800000, v56
	v_lshlrev_b32_e32 v58, 16, v58
	v_mul_f32_e32 v56, v59, v56
	v_mul_f32_e32 v53, v53, v58
	v_cvt_pk_bf16_f32 v56, v56, s0
	v_mul_f32_e32 v58, v52, v53
	ds_write_b16 v64, v56 offset:7920
	v_cvt_pk_bf16_f32 v53, v53, s0
	v_add_f32_e32 v56, v63, v57
	ds_read_u16 v57, v64 offset:8448
	ds_write_b16 v65, v53 offset:7920
	v_cvt_pk_bf16_f32 v53, v58, 0
	ds_read_u16 v58, v65 offset:8448
	v_mul_f32_e32 v59, 0x3fb8aa3b, v56
	v_mul_f32_e32 v56, 0xbfb8aa3b, v56
	v_exp_f32_e32 v59, v59
	v_exp_f32_e32 v56, v56
	s_waitcnt lgkmcnt(2)
	v_lshlrev_b32_e32 v57, 16, v57
	s_waitcnt lgkmcnt(0)
	v_lshlrev_b32_e32 v58, 16, v58
	v_mul_f32_e32 v57, 0x3d800000, v57
	v_mul_f32_e32 v57, v59, v57
	v_mul_f32_e32 v56, v56, v58
	v_mul_f32_e32 v58, v52, v56
	v_cvt_pk_bf16_f32 v57, v57, s0
	v_cvt_pk_bf16_f32 v56, v56, s0
	ds_write_b16 v64, v57 offset:8448
	ds_write_b16 v65, v56 offset:8448
	ds_read2st64_b32 v[56:57], v61 offset0:72 offset1:76
	ds_read_u16 v59, v64 offset:8976
	v_and_b32_e32 v53, 0xffff, v53
	v_cvt_pk_bf16_f32 v58, v58, 0
	s_waitcnt lgkmcnt(1)
	v_add_f32_e32 v56, v63, v56
	v_mul_f32_e32 v66, 0x3fb8aa3b, v56
	v_mul_f32_e32 v56, 0xbfb8aa3b, v56
	v_exp_f32_e32 v56, v56
	v_exp_f32_e32 v66, v66
	s_waitcnt lgkmcnt(0)
; __device__ __forceinline__ unsigned f2bf(float f) { return cvtpk(f, 0.f) & 0xffffu; }
; __device__ __forceinline__ void gla_prep_unit(const Params& P, LAS unsigned char* lds, int u) {
;     ...
;     for (int g8 = 0; g8 < 4; ++g8) { unsigned kdp[8];
; #pragma unroll
;         for (int e = 0; e < 8; ++e) { const int t = 32 * th + g8 * 8 + e; const float bb = Bs[t * 256 + c] + off;
;             const float qv = bf2f(QS[t * 264 + c]), kv = bf2f(KS[t * 264 + c]);
;             const float eb = __expf(bb), qt = qv * 0.0625f * eb, kt = kv * __expf(-bb), kd = kt * eblast;
;             QS[t * 264 + c] = (bf16)f2bf(qt); KS[t * 264 + c] = (bf16)f2bf(kt); kdp[e] = f2bf(kd); }
;         v4u o; o.x = kdp[0] | (kdp[1] << 16); o.y = kdp[2] | (kdp[3] << 16); o.z = kdp[4] | (kdp[5] << 16); o.w = kdp[6] | (kdp[7] << 16);
;         *(v4u*)(KDT + ((size_t)u * 256 + c) * 64 + 32 * th + g8 * 8) = o; }
	v_lshlrev_b32_e32 v59, 16, v59
	v_mul_f32_e32 v59, 0x3d800000, v59
	v_mul_f32_e32 v56, v56, v60
	v_mul_f32_e32 v59, v66, v59
	v_mul_f32_e32 v60, v52, v56
	v_cvt_pk_bf16_f32 v56, v56, s0
	v_cvt_pk_bf16_f32 v59, v59, s0
	ds_write_b16 v65, v56 offset:8976
	v_cvt_pk_bf16_f32 v56, v60, 0
	ds_write_b16 v64, v59 offset:8976
	v_and_b32_e32 v59, 0xffff, v56
	v_add_f32_e32 v56, v63, v57
	ds_read_u16 v57, v64 offset:9504
	v_mul_f32_e32 v66, 0x3fb8aa3b, v56
	v_exp_f32_e32 v66, v66
	ds_read_u16 v60, v65 offset:9504
	v_mul_f32_e32 v56, 0xbfb8aa3b, v56
	s_waitcnt lgkmcnt(1)
	v_lshlrev_b32_e32 v57, 16, v57
	v_mul_f32_e32 v57, 0x3d800000, v57
	v_mul_f32_e32 v57, v66, v57
	v_exp_f32_e32 v56, v56
	v_cvt_pk_bf16_f32 v57, v57, s0
	ds_write_b16 v64, v57 offset:9504
	ds_read_u16 v67, v65 offset:10032
	s_waitcnt lgkmcnt(2)
	v_lshlrev_b32_e32 v60, 16, v60
	v_mul_f32_e32 v56, v56, v60
	v_mul_f32_e32 v60, v52, v56
	v_cvt_pk_bf16_f32 v56, v56, s0
	ds_write_b16 v65, v56 offset:9504
	ds_read2st64_b32 v[56:57], v61 offset0:80 offset1:84
	ds_read_u16 v66, v64 offset:10032
	s_waitcnt lgkmcnt(3)
	v_lshlrev_b32_e32 v67, 16, v67
	v_cvt_pk_bf16_f32 v60, v60, 0
	s_waitcnt lgkmcnt(1)
	v_add_f32_e32 v56, v63, v56
	v_mul_f32_e32 v68, 0x3fb8aa3b, v56
	v_mul_f32_e32 v56, 0xbfb8aa3b, v56
	v_exp_f32_e32 v56, v56
	v_exp_f32_e32 v68, v68
	s_waitcnt lgkmcnt(0)
	v_lshlrev_b32_e32 v66, 16, v66
	v_mul_f32_e32 v66, 0x3d800000, v66
	v_mul_f32_e32 v56, v56, v67
	v_mul_f32_e32 v66, v68, v66
	v_mul_f32_e32 v67, v52, v56
	v_cvt_pk_bf16_f32 v56, v56, s0
	v_cvt_pk_bf16_f32 v66, v66, s0
	ds_write_b16 v65, v56 offset:10032
	v_cvt_pk_bf16_f32 v56, v67, 0
	ds_write_b16 v64, v66 offset:10032
	v_and_b32_e32 v66, 0xffff, v56
	v_add_f32_e32 v56, v63, v57
	ds_read_u16 v57, v64 offset:10560
	ds_read_u16 v67, v65 offset:10560
	ds_read_u16 v69, v65 offset:11088
	v_mul_f32_e32 v68, 0x3fb8aa3b, v56
	v_mul_f32_e32 v56, 0xbfb8aa3b, v56
	v_exp_f32_e32 v68, v68
	v_exp_f32_e32 v56, v56
	s_waitcnt lgkmcnt(2)
	v_lshlrev_b32_e32 v57, 16, v57
	s_waitcnt lgkmcnt(1)
	v_lshlrev_b32_e32 v67, 16, v67
	v_mul_f32_e32 v57, 0x3d800000, v57
	v_mul_f32_e32 v57, v68, v57
	v_mul_f32_e32 v56, v56, v67
	v_mul_f32_e32 v67, v52, v56
	v_cvt_pk_bf16_f32 v57, v57, s0
	v_cvt_pk_bf16_f32 v56, v56, s0
	ds_write_b16 v64, v57 offset:10560
	ds_write_b16 v65, v56 offset:10560
	ds_read2st64_b32 v[56:57], v61 offset0:88 offset1:92
	ds_read_u16 v68, v64 offset:11088
	s_waitcnt lgkmcnt(4)
	v_lshlrev_b32_e32 v69, 16, v69
	v_cvt_pk_bf16_f32 v67, v67, 0
	s_waitcnt lgkmcnt(1)
	v_add_f32_e32 v56, v63, v56
	v_mul_f32_e32 v70, 0x3fb8aa3b, v56
	v_mul_f32_e32 v56, 0xbfb8aa3b, v56
	v_exp_f32_e32 v56, v56
	v_exp_f32_e32 v70, v70
	s_waitcnt lgkmcnt(0)
	v_lshlrev_b32_e32 v68, 16, v68
	v_mul_f32_e32 v68, 0x3d800000, v68
	v_mul_f32_e32 v56, v56, v69
	v_mul_f32_e32 v68, v70, v68
	v_mul_f32_e32 v69, v52, v56
	v_cvt_pk_bf16_f32 v56, v56, s0
	v_cvt_pk_bf16_f32 v68, v68, s0
	ds_write_b16 v65, v56 offset:11088
	v_cvt_pk_bf16_f32 v56, v69, 0
	ds_write_b16 v64, v68 offset:11088
	v_and_b32_e32 v68, 0xffff, v56
	v_add_f32_e32 v56, v63, v57
	ds_read_u16 v57, v64 offset:11616
	v_mul_f32_e32 v70, 0x3fb8aa3b, v56
	v_exp_f32_e32 v70, v70
	ds_read_u16 v69, v65 offset:11616
	v_mul_f32_e32 v56, 0xbfb8aa3b, v56
	s_waitcnt lgkmcnt(1)
	v_lshlrev_b32_e32 v57, 16, v57
	v_mul_f32_e32 v57, 0x3d800000, v57
	v_exp_f32_e32 v56, v56
	v_mul_f32_e32 v57, v70, v57
	v_cvt_pk_bf16_f32 v57, v57, s0
	ds_write_b16 v64, v57 offset:11616
	v_lshl_or_b32 v57, v60, 16, v59
	ds_read_u16 v60, v65 offset:13200
	s_waitcnt lgkmcnt(2)
	v_lshlrev_b32_e32 v69, 16, v69
	v_mul_f32_e32 v56, v56, v69
	v_mul_f32_e32 v69, v52, v56
	v_cvt_pk_bf16_f32 v56, v56, s0
	v_cvt_pk_bf16_f32 v69, v69, 0
	ds_write_b16 v65, v56 offset:11616
	v_lshl_or_b32 v56, v58, 16, v53
	v_lshl_or_b32 v58, v67, 16, v66
	v_lshl_or_b32 v59, v69, 16, v68
	global_store_dwordx4 v[46:47], v[56:59], off offset:32
	ds_read2st64_b32 v[56:57], v61 offset0:96 offset1:100
	ds_read_u16 v58, v65 offset:12144
	s_waitcnt lgkmcnt(3)
	v_lshlrev_b32_e32 v60, 16, v60
	s_waitcnt lgkmcnt(1)
	v_add_f32_e32 v53, v63, v56
	ds_read_u16 v56, v64 offset:12144
	v_mul_f32_e32 v59, 0x3fb8aa3b, v53
	v_mul_f32_e32 v53, 0xbfb8aa3b, v53
	v_exp_f32_e32 v59, v59
	v_exp_f32_e32 v53, v53
	s_waitcnt lgkmcnt(0)
	v_lshlrev_b32_e32 v56, 16, v56
	v_lshlrev_b32_e32 v58, 16, v58
	v_mul_f32_e32 v56, 0x3d800000, v56
	v_mul_f32_e32 v56, v59, v56
	v_mul_f32_e32 v53, v53, v58
	v_mul_f32_e32 v58, v52, v53
	v_cvt_pk_bf16_f32 v56, v56, s0
	v_cvt_pk_bf16_f32 v53, v53, s0
	ds_write_b16 v64, v56 offset:12144
	ds_write_b16 v65, v53 offset:12144
	v_cvt_pk_bf16_f32 v53, v58, 0
	v_add_f32_e32 v56, v63, v57
	ds_read_u16 v58, v65 offset:12672
	ds_read_u16 v57, v64 offset:12672
	v_mul_f32_e32 v59, 0x3fb8aa3b, v56
	v_mul_f32_e32 v56, 0xbfb8aa3b, v56
	v_exp_f32_e32 v56, v56
	v_exp_f32_e32 v59, v59
	s_waitcnt lgkmcnt(1)
; __device__ __forceinline__ unsigned f2bf(float f) { return cvtpk(f, 0.f) & 0xffffu; }
; __device__ __forceinline__ void gla_prep_unit(const Params& P, LAS unsigned char* lds, int u) {
;     ...
;     for (int g8 = 0; g8 < 4; ++g8) { unsigned kdp[8];
; #pragma unroll
;         for (int e = 0; e < 8; ++e) { const int t = 32 * th + g8 * 8 + e; const float bb = Bs[t * 256 + c] + off;
;             const float qv = bf2f(QS[t * 264 + c]), kv = bf2f(KS[t * 264 + c]);
;             const float eb = __expf(bb), qt = qv * 0.0625f * eb, kt = kv * __expf(-bb), kd = kt * eblast;
;             QS[t * 264 + c] = (bf16)f2bf(qt); KS[t * 264 + c] = (bf16)f2bf(kt); kdp[e] = f2bf(kd); }
;         v4u o; o.x = kdp[0] | (kdp[1] << 16); o.y = kdp[2] | (kdp[3] << 16); o.z = kdp[4] | (kdp[5] << 16); o.w = kdp[6] | (kdp[7] << 16);
;         *(v4u*)(KDT + ((size_t)u * 256 + c) * 64 + 32 * th + g8 * 8) = o; }
;     if (th == 0) EL[(size_t)u * 256 + c] = eblast;
	v_lshlrev_b32_e32 v58, 16, v58
	s_waitcnt lgkmcnt(0)
	v_lshlrev_b32_e32 v57, 16, v57
	v_mul_f32_e32 v56, v56, v58
	v_mul_f32_e32 v57, 0x3d800000, v57
	v_mul_f32_e32 v58, v52, v56
	v_cvt_pk_bf16_f32 v56, v56, s0
	v_mul_f32_e32 v57, v59, v57
	ds_write_b16 v65, v56 offset:12672
	v_cvt_pk_bf16_f32 v56, v58, 0
	ds_read2st64_b32 v[58:59], v61 offset0:104 offset1:108
	v_cvt_pk_bf16_f32 v57, v57, s0
	ds_write_b16 v64, v57 offset:12672
	v_and_b32_e32 v53, 0xffff, v53
	v_lshl_or_b32 v56, v56, 16, v53
	s_waitcnt lgkmcnt(1)
	v_add_f32_e32 v57, v63, v58
	ds_read_u16 v58, v64 offset:13200
	v_mul_f32_e32 v66, 0x3fb8aa3b, v57
	v_mul_f32_e32 v57, 0xbfb8aa3b, v57
	v_exp_f32_e32 v66, v66
	v_exp_f32_e32 v57, v57
	s_waitcnt lgkmcnt(0)
	v_lshlrev_b32_e32 v58, 16, v58
	v_mul_f32_e32 v58, 0x3d800000, v58
	v_mul_f32_e32 v58, v66, v58
	v_mul_f32_e32 v57, v57, v60
	v_mul_f32_e32 v60, v52, v57
	v_cvt_pk_bf16_f32 v58, v58, s0
	v_cvt_pk_bf16_f32 v57, v57, s0
	ds_write_b16 v64, v58 offset:13200
	ds_write_b16 v65, v57 offset:13200
	v_cvt_pk_bf16_f32 v57, v60, 0
	v_add_f32_e32 v58, v63, v59
	ds_read_u16 v60, v65 offset:13728
	v_mul_f32_e32 v66, 0x3fb8aa3b, v58
	v_mul_f32_e32 v58, 0xbfb8aa3b, v58
	v_exp_f32_e32 v58, v58
	ds_read_u16 v59, v64 offset:13728
	s_waitcnt lgkmcnt(1)
	v_lshlrev_b32_e32 v60, 16, v60
	v_exp_f32_e32 v66, v66
	v_mul_f32_e32 v58, v58, v60
	v_mul_f32_e32 v60, v52, v58
	v_cvt_pk_bf16_f32 v58, v58, s0
	ds_write_b16 v65, v58 offset:13728
	v_cvt_pk_bf16_f32 v58, v60, 0
	ds_read_u16 v60, v64 offset:14256
	s_waitcnt lgkmcnt(2)
	v_lshlrev_b32_e32 v59, 16, v59
	v_mul_f32_e32 v59, 0x3d800000, v59
	v_mul_f32_e32 v59, v66, v59
	ds_read2st64_b32 v[66:67], v61 offset0:112 offset1:116
	v_cvt_pk_bf16_f32 v59, v59, s0
	ds_write_b16 v64, v59 offset:13728
	s_waitcnt lgkmcnt(2)
	v_lshlrev_b32_e32 v60, 16, v60
	v_mul_f32_e32 v60, 0x3d800000, v60
	s_waitcnt lgkmcnt(1)
	v_add_f32_e32 v59, v63, v66
	v_mul_f32_e32 v68, 0x3fb8aa3b, v59
	v_exp_f32_e32 v68, v68
	ds_read_u16 v66, v65 offset:14256
	v_mul_f32_e32 v59, 0xbfb8aa3b, v59
	v_exp_f32_e32 v59, v59
	v_mul_f32_e32 v60, v68, v60
	v_cvt_pk_bf16_f32 v60, v60, s0
	ds_write_b16 v64, v60 offset:14256
	v_add_f32_e32 v60, v63, v67
	ds_read_u16 v67, v65 offset:14784
	s_waitcnt lgkmcnt(2)
	v_lshlrev_b32_e32 v66, 16, v66
	v_mul_f32_e32 v59, v59, v66
	v_mul_f32_e32 v66, v52, v59
	v_cvt_pk_bf16_f32 v59, v59, s0
	ds_write_b16 v65, v59 offset:14256
	v_cvt_pk_bf16_f32 v59, v66, 0
	ds_read_u16 v66, v64 offset:14784
	v_mul_f32_e32 v68, 0x3fb8aa3b, v60
	v_mul_f32_e32 v60, 0xbfb8aa3b, v60
	v_exp_f32_e32 v60, v60
	v_exp_f32_e32 v68, v68
	s_waitcnt lgkmcnt(0)
	v_lshlrev_b32_e32 v66, 16, v66
	v_lshlrev_b32_e32 v67, 16, v67
	ds_read_b32 v61, v61 offset:30720
	v_mul_f32_e32 v66, 0x3d800000, v66
	v_mul_f32_e32 v60, v60, v67
	v_mul_f32_e32 v66, v68, v66
	v_mul_f32_e32 v67, v52, v60
	v_cvt_pk_bf16_f32 v60, v60, s0
	v_cvt_pk_bf16_f32 v66, v66, s0
	ds_write_b16 v65, v60 offset:14784
	ds_write_b16 v64, v66 offset:14784
	ds_read_u16 v66, v64 offset:15312
	s_waitcnt lgkmcnt(3)
	v_add_f32_e32 v61, v63, v61
	v_mul_f32_e32 v68, 0x3fb8aa3b, v61
	v_exp_f32_e32 v68, v68
	v_cvt_pk_bf16_f32 v60, v67, 0
	s_waitcnt lgkmcnt(0)
	v_lshlrev_b32_e32 v66, 16, v66
	v_mul_f32_e32 v66, 0x3d800000, v66
	ds_read_u16 v67, v65 offset:15312
	v_mul_f32_e32 v66, v68, v66
	v_mul_f32_e32 v61, 0xbfb8aa3b, v61
	v_cvt_pk_bf16_f32 v66, v66, s0
	v_exp_f32_e32 v61, v61
	ds_write_b16 v64, v66 offset:15312
	v_or_b32_e32 v64, 31, v55
	v_lshl_add_u32 v55, v64, 10, v62
	ds_read_b32 v55, v55
	s_waitcnt lgkmcnt(2)
	v_lshlrev_b32_e32 v67, 16, v67
	v_mul_f32_e32 v61, v61, v67
	v_mul_lo_u32 v62, v64, s27
	v_mul_f32_e32 v67, v52, v61
	v_cvt_pk_bf16_f32 v61, v61, s0
	v_add_lshl_u32 v35, v62, v35, 1
	ds_write_b16 v65, v61 offset:15312
	v_add_u32_e32 v62, s24, v35
	v_add_u32_e32 v35, s25, v35
	ds_read_u16 v64, v35
	s_waitcnt lgkmcnt(2)
	v_add_f32_e32 v55, v63, v55
	ds_read_u16 v63, v62
	v_mul_f32_e32 v65, 0x3fb8aa3b, v55
	v_mul_f32_e32 v55, 0xbfb8aa3b, v55
	v_exp_f32_e32 v55, v55
	v_exp_f32_e32 v65, v65
	s_waitcnt lgkmcnt(1)
	v_lshlrev_b32_e32 v64, 16, v64
	s_waitcnt lgkmcnt(0)
	v_lshlrev_b32_e32 v63, 16, v63
	v_mul_f32_e32 v55, v55, v64
	v_cvt_pk_bf16_f32 v61, v67, 0
	v_mul_f32_e32 v63, 0x3d800000, v63
	v_mul_f32_e32 v64, v52, v55
	v_cvt_pk_bf16_f32 v55, v55, s0
	v_and_b32_e32 v57, 0xffff, v57
	v_and_b32_e32 v59, 0xffff, v59
	v_and_b32_e32 v61, 0xffff, v61
	v_mul_f32_e32 v63, v65, v63
	ds_write_b16 v35, v55
	v_cvt_pk_bf16_f32 v35, v64, 0
	v_cvt_pk_bf16_f32 v63, v63, s0
	v_lshl_or_b32 v57, v58, 16, v57
	v_lshl_or_b32 v58, v60, 16, v59
	v_lshl_or_b32 v59, v35, 16, v61
	ds_write_b16 v62, v63
	global_store_dwordx4 v[46:47], v[56:59], off offset:48
	s_and_saveexec_b64 s[12:13], vcc
	s_cbranch_execz .LBB0_363
	s_lshl_b64 s[28:29], s[6:7], 10
	s_add_u32 s28, s57, s28
	s_addc_u32 s29, s63, s29
	global_store_dword v43, v52, s[28:29]
